# code placement: every MFMA block of the four GEMM K-loops starts at an address 4 mod 8 (s_nop pads in load segments)
# speedup vs baseline: 1.0053x; 1.0053x over previous
; #define PG8_STAGE(bufoff, gbase, voff) do { _Pragma("unroll") for (int _i = 0; _i < 2; ++_i) \
;         __builtin_amdgcn_global_load_lds((const unsigned*)((const char*)(gbase) + (voff)[_i]), (PG8_LAS unsigned*)(lds + (bufoff) + ldsw + _i * 8192), 16, 0, 0); } while (0)
; #define PG8_LDA(dst, b, h) do { _Pragma("unroll") for (int m = 0; m < 4; ++m) _Pragma("unroll") for (int k = 0; k < 2; ++k) dst[m][k] = *(const PG8_LAS bf16x8*)(lds + PG8_SA(b, h) + aoff + m * 2048 + k * 1024); } while (0)
; #define PG8_LDB(dst, b, h) do { _Pragma("unroll") for (int n = 0; n < 2; ++n) _Pragma("unroll") for (int k = 0; k < 2; ++k) dst[n][k] = *(const PG8_LAS bf16x8*)(lds + PG8_SB(b, h) + boff + n * 2048 + k * 1024); } while (0)
; #define PG8_MMA(ai, bj, At, Bt) do { __builtin_amdgcn_s_setprio(1); _Pragma("unroll") for (int m = 0; m < 4; ++m) _Pragma("unroll") for (int n = 0; n < 2; ++n) _Pragma("unroll") for (int k = 0; k < 2; ++k) \
;         acc[ai][bj][m][n] = __builtin_amdgcn_mfma_f32_16x16x32_bf16(Bt[n][k], At[m][k], acc[ai][bj][m][n], 0, 0, 0); __builtin_amdgcn_s_setprio(0); } while (0)
; #define PG8_WAIT_V(n) asm volatile("s_waitcnt vmcnt(" #n ")" ::: "memory")
; #define PG8_WAIT_L(n) asm volatile("s_waitcnt lgkmcnt(" #n ")" ::: "memory")
; #define PG8_BAR __builtin_amdgcn_s_barrier()
; #define PG8_SCHED __builtin_amdgcn_sched_barrier(0)
; template <class Epi, class Sched, bool ALIGN_EPI = false, bool SP2 = false>
; __device__ __forceinline__ void gemm_phase(PG8_LAS unsigned char* lds, const Gemm g, const Sched& S, const Epi& E) {
;     ...
;             const bool last = (t == nt - 2);
;             const char* a1 = cA + (size_t)(t + 1) * kstep;
;             const char* a2 = last ? nA : cA + (size_t)(t + 2) * kstep; const char* b2 = last ? nB : cB + (size_t)(t + 2) * kstep;
;             const char* a3 = a2 + kstep; const char* b3 = b2 + kstep;
;             if (last && has_next) S.a_ready(nxt);
;             if constexpr (SP2) {
;             PG8_LDB(B0, 0, 0); PG8_LDB(B1, 0, 1); PG8_SCHED; PG8_LDA(At, 0, 0); PG8_STAGE(PG8_SA(1, 1), a1 + hstep, voffA);
;             PG8_WAIT_V(8); PG8_WAIT_L(0); PG8_BAR; PG8_MMA(0, 0, At, B0); PG8_MMA(0, 1, At, B1); PG8_BAR; PG8_SCHED;
;             PG8_LDA(At, 0, 1); PG8_STAGE(PG8_SB(0, 0), b2, voffB); PG8_STAGE(PG8_SB(0, 1), b2 + hstep, voffB); PG8_STAGE(PG8_SA(0, 0), a2, voffA);
.LBB0_132:
	s_add_u32 s18, s46, 0xfffc0080
	s_addc_u32 s38, s47, -1
	s_add_i32 s39, 0, 0x10000
	s_cmp_eq_u32 s85, 12
	s_cselect_b32 s81, s33, s38
	s_cselect_b32 s80, s73, s18
	v_add_u32_e32 v0, s39, v176
	s_cselect_b32 s45, s75, s84
	s_cselect_b32 s44, s82, s83
	s_add_i32 s18, 0, 0x14000
	ds_read_b128 v[144:147], v0
	ds_read_b128 v[148:151], v0 offset:1024
	ds_read_b128 v[152:155], v0 offset:2048
	ds_read_b128 v[156:159], v0 offset:3072
	v_add_u32_e32 v0, s18, v176
	ds_read_b128 v[160:163], v0
	ds_read_b128 v[164:167], v0 offset:1024
	ds_read_b128 v[168:171], v0 offset:2048
	ds_read_b128 v[172:175], v0 offset:3072
	v_lshl_add_u64 v[218:219], s[46:47], 0, v[140:141]
	s_add_i32 m0, s92, 0xc000
	ds_read_b128 v[180:183], v178
	ds_read_b128 v[184:187], v178 offset:1024
	ds_read_b128 v[188:191], v178 offset:2048
	ds_read_b128 v[192:195], v178 offset:3072
	ds_read_b128 v[202:205], v178 offset:4096
	ds_read_b128 v[206:209], v178 offset:5120
	ds_read_b128 v[210:213], v178 offset:6144
	ds_read_b128 v[214:217], v178 offset:7168
	global_load_lds_dwordx4 v[218:219], off
	v_lshl_add_u64 v[218:219], s[46:47], 0, v[142:143]
	s_add_i32 m0, s92, 0xe000
	s_nop 0
	global_load_lds_dwordx4 v[218:219], off
	s_nop 0
	s_waitcnt vmcnt(8)
	s_waitcnt lgkmcnt(0)
	s_barrier
	s_setprio 1
	v_mfma_f32_16x16x32_bf16 v[118:121], v[144:147], v[180:183], v[118:121]
	v_mfma_f32_16x16x32_bf16 v[118:121], v[148:151], v[184:187], v[118:121]
	v_mfma_f32_16x16x32_bf16 v[102:105], v[144:147], v[188:191], v[102:105]
	v_mfma_f32_16x16x32_bf16 v[102:105], v[148:151], v[192:195], v[102:105]
	v_mfma_f32_16x16x32_bf16 v[86:89], v[144:147], v[202:205], v[86:89]
	v_mfma_f32_16x16x32_bf16 v[86:89], v[148:151], v[206:209], v[86:89]
	v_mfma_f32_16x16x32_bf16 v[70:73], v[144:147], v[210:213], v[70:73]
	v_mfma_f32_16x16x32_bf16 v[70:73], v[148:151], v[214:217], v[70:73]
	v_mfma_f32_16x16x32_bf16 v[114:117], v[152:155], v[180:183], v[114:117]
	v_mfma_f32_16x16x32_bf16 v[114:117], v[156:159], v[184:187], v[114:117]
	v_mfma_f32_16x16x32_bf16 v[98:101], v[152:155], v[188:191], v[98:101]
	v_mfma_f32_16x16x32_bf16 v[98:101], v[156:159], v[192:195], v[98:101]
	v_mfma_f32_16x16x32_bf16 v[82:85], v[152:155], v[202:205], v[82:85]
	v_mfma_f32_16x16x32_bf16 v[82:85], v[156:159], v[206:209], v[82:85]
	v_mfma_f32_16x16x32_bf16 v[66:69], v[152:155], v[210:213], v[66:69]
	v_mfma_f32_16x16x32_bf16 v[66:69], v[156:159], v[214:217], v[66:69]
	v_mfma_f32_16x16x32_bf16 v[126:129], v[160:163], v[180:183], v[126:129]
	v_mfma_f32_16x16x32_bf16 v[126:129], v[164:167], v[184:187], v[126:129]
	v_mfma_f32_16x16x32_bf16 v[110:113], v[160:163], v[188:191], v[110:113]
	v_mfma_f32_16x16x32_bf16 v[110:113], v[164:167], v[192:195], v[110:113]
	v_mfma_f32_16x16x32_bf16 v[94:97], v[160:163], v[202:205], v[94:97]
	v_mfma_f32_16x16x32_bf16 v[94:97], v[164:167], v[206:209], v[94:97]
	v_mfma_f32_16x16x32_bf16 v[78:81], v[160:163], v[210:213], v[78:81]
	v_mfma_f32_16x16x32_bf16 v[78:81], v[164:167], v[214:217], v[78:81]
	v_mfma_f32_16x16x32_bf16 v[122:125], v[168:171], v[180:183], v[122:125]
	v_mfma_f32_16x16x32_bf16 v[122:125], v[172:175], v[184:187], v[122:125]
	v_mfma_f32_16x16x32_bf16 v[106:109], v[168:171], v[188:191], v[106:109]
	v_mfma_f32_16x16x32_bf16 v[106:109], v[172:175], v[192:195], v[106:109]
	v_mfma_f32_16x16x32_bf16 v[90:93], v[168:171], v[202:205], v[90:93]
	v_mfma_f32_16x16x32_bf16 v[90:93], v[172:175], v[206:209], v[90:93]
	v_mfma_f32_16x16x32_bf16 v[74:77], v[168:171], v[210:213], v[74:77]
	v_mfma_f32_16x16x32_bf16 v[74:77], v[172:175], v[214:217], v[74:77]
	s_setprio 0
	s_barrier
	s_add_i32 s38, s39, s91
	v_lshl_add_u64 v[218:219], s[44:45], 0, v[134:135]
	s_mov_b32 m0, s38
	ds_read_b128 v[180:183], v178 offset:16384
	ds_read_b128 v[184:187], v178 offset:17408
	ds_read_b128 v[188:191], v178 offset:18432
	ds_read_b128 v[192:195], v178 offset:19456
	ds_read_b128 v[202:205], v178 offset:20480
	ds_read_b128 v[206:209], v178 offset:21504
	ds_read_b128 v[210:213], v178 offset:22528
	ds_read_b128 v[214:217], v178 offset:23552
	global_load_lds_dwordx4 v[218:219], off
	s_add_i32 m0, s38, 0x2000
	s_add_u32 s38, s44, 0x40000
	v_lshl_add_u64 v[220:221], s[44:45], 0, v[130:131]
	s_addc_u32 s39, s45, 0
	s_add_i32 s18, s18, s91
	global_load_lds_dwordx4 v[220:221], off
	v_lshl_add_u64 v[222:223], s[38:39], 0, v[134:135]
	s_mov_b32 m0, s18
	v_lshl_add_u64 v[224:225], s[80:81], 0, v[132:133]
	global_load_lds_dwordx4 v[222:223], off
	v_lshl_add_u64 v[222:223], s[38:39], 0, v[130:131]
	s_add_i32 m0, s18, 0x2000
	s_nop 0
	global_load_lds_dwordx4 v[222:223], off
	v_lshl_add_u64 v[222:223], s[80:81], 0, v[136:137]
	s_mov_b32 m0, s92
	s_nop 0
	global_load_lds_dwordx4 v[222:223], off
	s_mov_b32 m0, s93
	s_nop 0
	global_load_lds_dwordx4 v[224:225], off
	s_waitcnt vmcnt(8)
	s_waitcnt lgkmcnt(0)
	s_barrier
; #define PG8_STAGE(bufoff, gbase, voff) do { _Pragma("unroll") for (int _i = 0; _i < 2; ++_i) \
;         __builtin_amdgcn_global_load_lds((const unsigned*)((const char*)(gbase) + (voff)[_i]), (PG8_LAS unsigned*)(lds + (bufoff) + ldsw + _i * 8192), 16, 0, 0); } while (0)
; #define PG8_LDA(dst, b, h) do { _Pragma("unroll") for (int m = 0; m < 4; ++m) _Pragma("unroll") for (int k = 0; k < 2; ++k) dst[m][k] = *(const PG8_LAS bf16x8*)(lds + PG8_SA(b, h) + aoff + m * 2048 + k * 1024); } while (0)
; #define PG8_LDB(dst, b, h) do { _Pragma("unroll") for (int n = 0; n < 2; ++n) _Pragma("unroll") for (int k = 0; k < 2; ++k) dst[n][k] = *(const PG8_LAS bf16x8*)(lds + PG8_SB(b, h) + boff + n * 2048 + k * 1024); } while (0)
; #define PG8_MMA(ai, bj, At, Bt) do { __builtin_amdgcn_s_setprio(1); _Pragma("unroll") for (int m = 0; m < 4; ++m) _Pragma("unroll") for (int n = 0; n < 2; ++n) _Pragma("unroll") for (int k = 0; k < 2; ++k) \
;         acc[ai][bj][m][n] = __builtin_amdgcn_mfma_f32_16x16x32_bf16(Bt[n][k], At[m][k], acc[ai][bj][m][n], 0, 0, 0); __builtin_amdgcn_s_setprio(0); } while (0)
; #define PG8_WAIT_V(n) asm volatile("s_waitcnt vmcnt(" #n ")" ::: "memory")
; #define PG8_WAIT_L(n) asm volatile("s_waitcnt lgkmcnt(" #n ")" ::: "memory")
; #define PG8_BAR __builtin_amdgcn_s_barrier()
; #define PG8_SCHED __builtin_amdgcn_sched_barrier(0)
; template <class Epi, class Sched, bool ALIGN_EPI = false, bool SP2 = false>
; __device__ __forceinline__ void gemm_phase(PG8_LAS unsigned char* lds, const Gemm g, const Sched& S, const Epi& E) {
;     ...
;             PG8_WAIT_V(8); PG8_WAIT_L(0); PG8_BAR; PG8_MMA(1, 0, At, B0); PG8_MMA(1, 1, At, B1); PG8_BAR; PG8_SCHED;
;             PG8_LDB(B0, 1, 0); PG8_LDB(B1, 1, 1); PG8_SCHED; PG8_LDA(At, 1, 0); PG8_STAGE(PG8_SA(0, 1), a2 + hstep, voffA);
;             PG8_WAIT_V(8); PG8_WAIT_L(0); PG8_BAR; PG8_MMA(0, 0, At, B0); PG8_MMA(0, 1, At, B1); PG8_BAR; PG8_SCHED;
	s_setprio 1
	v_mfma_f32_16x16x32_bf16 v[54:57], v[144:147], v[180:183], v[54:57]
	v_mfma_f32_16x16x32_bf16 v[54:57], v[148:151], v[184:187], v[54:57]
	v_mfma_f32_16x16x32_bf16 v[38:41], v[144:147], v[188:191], v[38:41]
	v_mfma_f32_16x16x32_bf16 v[38:41], v[148:151], v[192:195], v[38:41]
	v_mfma_f32_16x16x32_bf16 v[22:25], v[144:147], v[202:205], v[22:25]
	v_mfma_f32_16x16x32_bf16 v[22:25], v[148:151], v[206:209], v[22:25]
	v_mfma_f32_16x16x32_bf16 v[6:9], v[144:147], v[210:213], v[6:9]
	v_mfma_f32_16x16x32_bf16 v[6:9], v[148:151], v[214:217], v[6:9]
	v_mfma_f32_16x16x32_bf16 v[50:53], v[152:155], v[180:183], v[50:53]
	v_mfma_f32_16x16x32_bf16 v[50:53], v[156:159], v[184:187], v[50:53]
	v_mfma_f32_16x16x32_bf16 v[34:37], v[152:155], v[188:191], v[34:37]
	v_mfma_f32_16x16x32_bf16 v[34:37], v[156:159], v[192:195], v[34:37]
	v_mfma_f32_16x16x32_bf16 v[18:21], v[152:155], v[202:205], v[18:21]
	v_mfma_f32_16x16x32_bf16 v[18:21], v[156:159], v[206:209], v[18:21]
	v_mfma_f32_16x16x32_bf16 v[2:5], v[152:155], v[210:213], v[2:5]
	v_mfma_f32_16x16x32_bf16 v[2:5], v[156:159], v[214:217], v[2:5]
	v_mfma_f32_16x16x32_bf16 v[62:65], v[160:163], v[180:183], v[62:65]
	v_mfma_f32_16x16x32_bf16 v[62:65], v[164:167], v[184:187], v[62:65]
	v_mfma_f32_16x16x32_bf16 v[46:49], v[160:163], v[188:191], v[46:49]
	v_mfma_f32_16x16x32_bf16 v[46:49], v[164:167], v[192:195], v[46:49]
	v_mfma_f32_16x16x32_bf16 v[30:33], v[160:163], v[202:205], v[30:33]
	v_mfma_f32_16x16x32_bf16 v[30:33], v[164:167], v[206:209], v[30:33]
	v_mfma_f32_16x16x32_bf16 v[10:13], v[160:163], v[210:213], v[10:13]
	v_mfma_f32_16x16x32_bf16 v[10:13], v[164:167], v[214:217], v[10:13]
	v_mfma_f32_16x16x32_bf16 v[58:61], v[168:171], v[180:183], v[58:61]
	v_mfma_f32_16x16x32_bf16 v[58:61], v[172:175], v[184:187], v[58:61]
	v_mfma_f32_16x16x32_bf16 v[42:45], v[168:171], v[188:191], v[42:45]
	v_mfma_f32_16x16x32_bf16 v[42:45], v[172:175], v[192:195], v[42:45]
	v_mfma_f32_16x16x32_bf16 v[26:29], v[168:171], v[202:205], v[26:29]
	v_mfma_f32_16x16x32_bf16 v[26:29], v[172:175], v[206:209], v[26:29]
	v_mfma_f32_16x16x32_bf16 v[14:17], v[168:171], v[210:213], v[14:17]
	v_mfma_f32_16x16x32_bf16 v[14:17], v[172:175], v[214:217], v[14:17]
	s_setprio 0
	s_barrier
	s_add_i32 s18, 0, 0x18000
	v_add_u32_e32 v0, s18, v176
	s_add_i32 vcc_lo, 0, 0x1c000
	ds_read_b128 v[144:147], v0
	ds_read_b128 v[148:151], v0 offset:1024
	ds_read_b128 v[152:155], v0 offset:2048
	ds_read_b128 v[156:159], v0 offset:3072
	v_add_u32_e32 v0, vcc_lo, v176
	ds_read_b128 v[160:163], v0
	ds_read_b128 v[164:167], v0 offset:1024
	ds_read_b128 v[168:171], v0 offset:2048
	ds_read_b128 v[172:175], v0 offset:3072
	s_add_u32 s38, s80, 0x40000
	s_addc_u32 s39, s81, 0
	s_mov_b32 m0, s94
	v_lshl_add_u64 v[226:227], s[38:39], 0, v[136:137]
	ds_read_b128 v[180:183], v178 offset:32768
	ds_read_b128 v[184:187], v178 offset:33792
	ds_read_b128 v[188:191], v178 offset:34816
	ds_read_b128 v[192:195], v178 offset:35840
	ds_read_b128 v[202:205], v178 offset:36864
	ds_read_b128 v[206:209], v178 offset:37888
	ds_read_b128 v[210:213], v178 offset:38912
	ds_read_b128 v[214:217], v178 offset:39936
	global_load_lds_dwordx4 v[226:227], off
	v_lshl_add_u64 v[226:227], s[38:39], 0, v[132:133]
	s_mov_b32 m0, s95
	s_nop 0
	global_load_lds_dwordx4 v[226:227], off
	s_waitcnt vmcnt(8)
	s_waitcnt lgkmcnt(0)
	s_barrier
	s_setprio 1
	v_mfma_f32_16x16x32_bf16 v[118:121], v[144:147], v[180:183], v[118:121]
	v_mfma_f32_16x16x32_bf16 v[118:121], v[148:151], v[184:187], v[118:121]
	v_mfma_f32_16x16x32_bf16 v[102:105], v[144:147], v[188:191], v[102:105]
	v_mfma_f32_16x16x32_bf16 v[102:105], v[148:151], v[192:195], v[102:105]
	v_mfma_f32_16x16x32_bf16 v[86:89], v[144:147], v[202:205], v[86:89]
	v_mfma_f32_16x16x32_bf16 v[86:89], v[148:151], v[206:209], v[86:89]
	v_mfma_f32_16x16x32_bf16 v[70:73], v[144:147], v[210:213], v[70:73]
	v_mfma_f32_16x16x32_bf16 v[70:73], v[148:151], v[214:217], v[70:73]
	v_mfma_f32_16x16x32_bf16 v[114:117], v[152:155], v[180:183], v[114:117]
	v_mfma_f32_16x16x32_bf16 v[114:117], v[156:159], v[184:187], v[114:117]
	v_mfma_f32_16x16x32_bf16 v[98:101], v[152:155], v[188:191], v[98:101]
	v_mfma_f32_16x16x32_bf16 v[98:101], v[156:159], v[192:195], v[98:101]
	v_mfma_f32_16x16x32_bf16 v[82:85], v[152:155], v[202:205], v[82:85]
	v_mfma_f32_16x16x32_bf16 v[82:85], v[156:159], v[206:209], v[82:85]
	v_mfma_f32_16x16x32_bf16 v[66:69], v[152:155], v[210:213], v[66:69]
	v_mfma_f32_16x16x32_bf16 v[66:69], v[156:159], v[214:217], v[66:69]
	v_mfma_f32_16x16x32_bf16 v[126:129], v[160:163], v[180:183], v[126:129]
	v_mfma_f32_16x16x32_bf16 v[126:129], v[164:167], v[184:187], v[126:129]
	v_mfma_f32_16x16x32_bf16 v[110:113], v[160:163], v[188:191], v[110:113]
	v_mfma_f32_16x16x32_bf16 v[110:113], v[164:167], v[192:195], v[110:113]
	v_mfma_f32_16x16x32_bf16 v[94:97], v[160:163], v[202:205], v[94:97]
	v_mfma_f32_16x16x32_bf16 v[94:97], v[164:167], v[206:209], v[94:97]
	v_mfma_f32_16x16x32_bf16 v[78:81], v[160:163], v[210:213], v[78:81]
	v_mfma_f32_16x16x32_bf16 v[78:81], v[164:167], v[214:217], v[78:81]
	v_mfma_f32_16x16x32_bf16 v[122:125], v[168:171], v[180:183], v[122:125]
	v_mfma_f32_16x16x32_bf16 v[122:125], v[172:175], v[184:187], v[122:125]
	v_mfma_f32_16x16x32_bf16 v[106:109], v[168:171], v[188:191], v[106:109]
	v_mfma_f32_16x16x32_bf16 v[106:109], v[172:175], v[192:195], v[106:109]
	v_mfma_f32_16x16x32_bf16 v[90:93], v[168:171], v[202:205], v[90:93]
	v_mfma_f32_16x16x32_bf16 v[90:93], v[172:175], v[206:209], v[90:93]
	v_mfma_f32_16x16x32_bf16 v[74:77], v[168:171], v[210:213], v[74:77]
	v_mfma_f32_16x16x32_bf16 v[74:77], v[172:175], v[214:217], v[74:77]
	s_setprio 0
	s_barrier
; #define PG8_STAGE(bufoff, gbase, voff) do { _Pragma("unroll") for (int _i = 0; _i < 2; ++_i) \
;         __builtin_amdgcn_global_load_lds((const unsigned*)((const char*)(gbase) + (voff)[_i]), (PG8_LAS unsigned*)(lds + (bufoff) + ldsw + _i * 8192), 16, 0, 0); } while (0)
; #define PG8_LDA(dst, b, h) do { _Pragma("unroll") for (int m = 0; m < 4; ++m) _Pragma("unroll") for (int k = 0; k < 2; ++k) dst[m][k] = *(const PG8_LAS bf16x8*)(lds + PG8_SA(b, h) + aoff + m * 2048 + k * 1024); } while (0)
; #define PG8_MMA(ai, bj, At, Bt) do { __builtin_amdgcn_s_setprio(1); _Pragma("unroll") for (int m = 0; m < 4; ++m) _Pragma("unroll") for (int n = 0; n < 2; ++n) _Pragma("unroll") for (int k = 0; k < 2; ++k) \
;         acc[ai][bj][m][n] = __builtin_amdgcn_mfma_f32_16x16x32_bf16(Bt[n][k], At[m][k], acc[ai][bj][m][n], 0, 0, 0); __builtin_amdgcn_s_setprio(0); } while (0)
; #define PG8_WAIT_V(n) asm volatile("s_waitcnt vmcnt(" #n ")" ::: "memory")
; #define PG8_WAIT_L(n) asm volatile("s_waitcnt lgkmcnt(" #n ")" ::: "memory")
; #define PG8_BAR __builtin_amdgcn_s_barrier()
; #define PG8_SCHED __builtin_amdgcn_sched_barrier(0)
; template <class Epi, class Sched, bool ALIGN_EPI = false, bool SP2 = false>
; __device__ __forceinline__ void gemm_phase(PG8_LAS unsigned char* lds, const Gemm g, const Sched& S, const Epi& E) {
;     ...
;         for (int t = 0; t < nt; t += 2) {
;     ...
;             PG8_LDA(At, 1, 1); PG8_STAGE(PG8_SB(1, 0), b3, voffB); PG8_STAGE(PG8_SB(1, 1), b3 + hstep, voffB); PG8_STAGE(PG8_SA(1, 0), a3, voffA);
;             PG8_WAIT_V(8); PG8_WAIT_L(0); PG8_BAR; PG8_MMA(1, 0, At, B0); PG8_MMA(1, 1, At, B1); PG8_BAR; PG8_SCHED;
	s_add_i32 s18, s18, s91
	v_lshl_add_u64 v[218:219], v[218:219], 0, s[30:31]
	s_mov_b32 m0, s18
	ds_read_b128 v[180:183], v178 offset:49152
	ds_read_b128 v[184:187], v178 offset:50176
	ds_read_b128 v[188:191], v178 offset:51200
	ds_read_b128 v[192:195], v178 offset:52224
	ds_read_b128 v[202:205], v178 offset:53248
	ds_read_b128 v[206:209], v178 offset:54272
	ds_read_b128 v[210:213], v178 offset:55296
	ds_read_b128 v[214:217], v178 offset:56320
	global_load_lds_dwordx4 v[218:219], off
	s_add_i32 m0, s18, 0x2000
	s_add_u32 s38, s44, 0x40080
	v_lshl_add_u64 v[218:219], v[220:221], 0, s[30:31]
	s_addc_u32 s39, s45, 0
	s_add_i32 s18, vcc_lo, s91
	global_load_lds_dwordx4 v[218:219], off
	v_lshl_add_u64 v[218:219], s[38:39], 0, v[134:135]
	s_mov_b32 m0, s18
	s_nop 0
	global_load_lds_dwordx4 v[218:219], off
	v_lshl_add_u64 v[218:219], s[38:39], 0, v[130:131]
	s_add_i32 m0, s18, 0x2000
	s_nop 0
	global_load_lds_dwordx4 v[218:219], off
	v_lshl_add_u64 v[218:219], v[222:223], 0, s[30:31]
	s_mov_b32 m0, s7
	s_nop 0
	global_load_lds_dwordx4 v[218:219], off
	v_lshl_add_u64 v[218:219], v[224:225], 0, s[30:31]
	s_mov_b32 m0, s96
	s_nop 0
	global_load_lds_dwordx4 v[218:219], off
	s_nop 0
	s_waitcnt vmcnt(8)
	s_waitcnt lgkmcnt(0)
	s_barrier
	s_setprio 1
	v_mfma_f32_16x16x32_bf16 v[54:57], v[144:147], v[180:183], v[54:57]
	v_mfma_f32_16x16x32_bf16 v[54:57], v[148:151], v[184:187], v[54:57]
	v_mfma_f32_16x16x32_bf16 v[38:41], v[144:147], v[188:191], v[38:41]
	v_mfma_f32_16x16x32_bf16 v[38:41], v[148:151], v[192:195], v[38:41]
	v_mfma_f32_16x16x32_bf16 v[22:25], v[144:147], v[202:205], v[22:25]
	v_mfma_f32_16x16x32_bf16 v[22:25], v[148:151], v[206:209], v[22:25]
	v_mfma_f32_16x16x32_bf16 v[6:9], v[144:147], v[210:213], v[6:9]
	v_mfma_f32_16x16x32_bf16 v[6:9], v[148:151], v[214:217], v[6:9]
	v_mfma_f32_16x16x32_bf16 v[50:53], v[152:155], v[180:183], v[50:53]
	v_mfma_f32_16x16x32_bf16 v[50:53], v[156:159], v[184:187], v[50:53]
	v_mfma_f32_16x16x32_bf16 v[34:37], v[152:155], v[188:191], v[34:37]
	v_mfma_f32_16x16x32_bf16 v[34:37], v[156:159], v[192:195], v[34:37]
	v_mfma_f32_16x16x32_bf16 v[18:21], v[152:155], v[202:205], v[18:21]
	v_mfma_f32_16x16x32_bf16 v[18:21], v[156:159], v[206:209], v[18:21]
	v_mfma_f32_16x16x32_bf16 v[2:5], v[152:155], v[210:213], v[2:5]
	v_mfma_f32_16x16x32_bf16 v[2:5], v[156:159], v[214:217], v[2:5]
	v_mfma_f32_16x16x32_bf16 v[62:65], v[160:163], v[180:183], v[62:65]
	v_mfma_f32_16x16x32_bf16 v[62:65], v[164:167], v[184:187], v[62:65]
	v_mfma_f32_16x16x32_bf16 v[46:49], v[160:163], v[188:191], v[46:49]
	v_mfma_f32_16x16x32_bf16 v[46:49], v[164:167], v[192:195], v[46:49]
	v_mfma_f32_16x16x32_bf16 v[30:33], v[160:163], v[202:205], v[30:33]
	v_mfma_f32_16x16x32_bf16 v[30:33], v[164:167], v[206:209], v[30:33]
	v_mfma_f32_16x16x32_bf16 v[10:13], v[160:163], v[210:213], v[10:13]
	v_mfma_f32_16x16x32_bf16 v[10:13], v[164:167], v[214:217], v[10:13]
	v_mfma_f32_16x16x32_bf16 v[58:61], v[168:171], v[180:183], v[58:61]
	v_mfma_f32_16x16x32_bf16 v[58:61], v[172:175], v[184:187], v[58:61]
	v_mfma_f32_16x16x32_bf16 v[42:45], v[168:171], v[188:191], v[42:45]
	v_mfma_f32_16x16x32_bf16 v[42:45], v[172:175], v[192:195], v[42:45]
	v_mfma_f32_16x16x32_bf16 v[26:29], v[168:171], v[202:205], v[26:29]
	v_mfma_f32_16x16x32_bf16 v[26:29], v[172:175], v[206:209], v[26:29]
	v_mfma_f32_16x16x32_bf16 v[14:17], v[168:171], v[210:213], v[14:17]
	v_mfma_f32_16x16x32_bf16 v[14:17], v[172:175], v[214:217], v[14:17]
	s_setprio 0
	s_barrier
	s_add_i32 s85, s85, 2
	s_add_u32 s46, s46, 0x100
	s_addc_u32 s47, s47, 0
	s_add_u32 s83, s83, 0x100
	s_addc_u32 s84, s84, 0
	s_cmp_gt_u32 s85, 13
	s_cbranch_scc0 .LBB0_132
	s_and_b64 vcc, exec, s[10:11]
	s_cbranch_vccz .LBB0_135
	s_barrier
